# pool_unit staging: the ten 16-byte row loads per lane are requested together and written to LDS as they arrive (was load, wait, write ten times)
# speedup vs baseline: 1.0012x; 1.0012x over previous
.LBB0_990:
	v_mov_b32_e32 v0, v221
	v_readlane_b32 s1, v252, 7
	s_ashr_i32 s0, s13, 5
	s_movk_i32 s2, 0x1400
	v_or_b32_e32 v4, s1, v0
	s_ashr_i32 s1, s0, 31
	v_cmp_gt_i32_e32 vcc, s2, v4
	s_barrier
	s_and_saveexec_b64 s[2:3], vcc
	s_cbranch_execz .LBB0_995
	s_lshl_b32 s4, s13, 6
	s_and_b32 s14, s4, 0x7c0
	s_lshl_b64 s[4:5], s[0:1], 21
	s_add_u32 s4, s8, s4
	s_addc_u32 s5, s9, s5
	s_add_i32 s14, s14, -16
	v_lshlrev_b32_e32 v0, 4, v0
	v_and_b32_e32 v5, 0x3f0, v0
	v_lshrrev_b32_e32 v9, 6, v4
	v_add_u32_e32 v8, s14, v9
	v_lshl_add_u32 v60, v8, 10, v5
	v_lshl_add_u32 v7, v9, 10, v5
	v_add_u32_e32 v10, 0x10000, v7
	v_add_u32_e32 v61, 0x2000, v60
	v_add_u32_e32 v62, 0x4000, v60
	v_add_u32_e32 v63, 0x6000, v60
	v_add_u32_e32 v64, 0x8000, v60
	v_add_u32_e32 v65, 0xa000, v60
	v_add_u32_e32 v66, 0xc000, v60
	v_add_u32_e32 v67, 0xe000, v60
	v_add_u32_e32 v68, 0x10000, v60
	v_add_u32_e32 v69, 0x12000, v60
	s_cmp_lt_i32 s14, 0
	s_cbranch_scc1 .Lpool_zero
	global_load_dwordx4 v[20:23], v60, s[4:5]
	global_load_dwordx4 v[24:27], v61, s[4:5]
	s_branch .Lpool_ld2
.Lpool_zero:
	v_mov_b32_e32 v20, 0
	v_mov_b32_e32 v21, 0
	v_mov_b32_e32 v22, 0
	v_mov_b32_e32 v23, 0
	v_mov_b32_e32 v24, 0
	v_mov_b32_e32 v25, 0
	v_mov_b32_e32 v26, 0
	v_mov_b32_e32 v27, 0
.Lpool_ld2:
	global_load_dwordx4 v[28:31], v62, s[4:5]
	global_load_dwordx4 v[32:35], v63, s[4:5]
	global_load_dwordx4 v[36:39], v64, s[4:5]
	global_load_dwordx4 v[40:43], v65, s[4:5]
	global_load_dwordx4 v[44:47], v66, s[4:5]
	global_load_dwordx4 v[48:51], v67, s[4:5]
	global_load_dwordx4 v[52:55], v68, s[4:5]
	global_load_dwordx4 v[56:59], v69, s[4:5]
	s_waitcnt vmcnt(9)
	ds_write_b128 v7, v[20:23]
	s_waitcnt vmcnt(8)
	ds_write_b128 v7, v[24:27] offset:8192
	s_waitcnt vmcnt(7)
	ds_write_b128 v7, v[28:31] offset:16384
	s_waitcnt vmcnt(6)
	ds_write_b128 v7, v[32:35] offset:24576
	s_waitcnt vmcnt(5)
	ds_write_b128 v7, v[36:39] offset:32768
	s_waitcnt vmcnt(4)
	ds_write_b128 v7, v[40:43] offset:40960
	s_waitcnt vmcnt(3)
	ds_write_b128 v7, v[44:47] offset:49152
	s_waitcnt vmcnt(2)
	ds_write_b128 v7, v[48:51] offset:57344
	s_waitcnt vmcnt(1)
	ds_write_b128 v10, v[52:55]
	s_waitcnt vmcnt(0)
	ds_write_b128 v10, v[56:59] offset:8192
